# GEMM K-loops: leading half retires its LDS-DMA loads after the two MFMA blocks (before its barrier b) instead of before barrier a
# baseline (speedup 1.0000x reference)
; #define PG8_STAGE(bufoff, gbase, voff) do { _Pragma("unroll") for (int _i = 0; _i < 2; ++_i) \
;         __builtin_amdgcn_global_load_lds((const unsigned*)((const char*)(gbase) + (voff)[_i]), (PG8_LAS unsigned*)(lds + (bufoff) + ldsw + _i * 8192), 16, 0, 0); } while (0)
; #define PG8_LDA(dst, b, h) do { _Pragma("unroll") for (int m = 0; m < 4; ++m) _Pragma("unroll") for (int k = 0; k < 2; ++k) dst[m][k] = *(const PG8_LAS bf16x8*)(lds + PG8_SA(b, h) + aoff + m * 2048 + k * 1024); } while (0)
; #define PG8_LDB(dst, b, h) do { _Pragma("unroll") for (int n = 0; n < 2; ++n) _Pragma("unroll") for (int k = 0; k < 2; ++k) dst[n][k] = *(const PG8_LAS bf16x8*)(lds + PG8_SB(b, h) + boff + n * 2048 + k * 1024); } while (0)
; #define PG8_MMA(ai, bj, At, Bt) do { __builtin_amdgcn_s_setprio(1); _Pragma("unroll") for (int m = 0; m < 4; ++m) _Pragma("unroll") for (int n = 0; n < 2; ++n) _Pragma("unroll") for (int k = 0; k < 2; ++k) \
;         acc[ai][bj][m][n] = __builtin_amdgcn_mfma_f32_16x16x32_bf16(Bt[n][k], At[m][k], acc[ai][bj][m][n], 0, 0, 0); __builtin_amdgcn_s_setprio(0); } while (0)
; #define PG8_WAIT_V(n) asm volatile("s_waitcnt vmcnt(" #n ")" ::: "memory")
; #define PG8_WAIT_L(n) asm volatile("s_waitcnt lgkmcnt(" #n ")" ::: "memory")
; #define PG8_BAR __builtin_amdgcn_s_barrier()
; #define PG8_SCHED __builtin_amdgcn_sched_barrier(0)
; template <class Epi, class Sched, bool ALIGN_EPI = false, bool SP2 = false>
; __device__ __forceinline__ void gemm_phase(PG8_LAS unsigned char* lds, const Gemm g, const Sched& S, const Epi& E, int tid_in) {
;     ...
;             PG8_LDB(B0, 0, 0); PG8_LDB(B1, 0, 1); PG8_SCHED; PG8_LDA(At, 0, 0); PG8_STAGE(PG8_SA(1, 1), a1 + hstep, voffA);
;             PG8_WAIT_V(8); PG8_WAIT_L(0); PG8_BAR; PG8_MMA(0, 0, At, B0); PG8_MMA(0, 1, At, B1); PG8_BAR; PG8_SCHED;
;             PG8_LDA(At, 0, 1); PG8_STAGE(PG8_SB(0, 0), b2, voffB); PG8_STAGE(PG8_SB(0, 1), b2 + hstep, voffB); PG8_STAGE(PG8_SA(0, 0), a2, voffA);
;             PG8_WAIT_V(8); PG8_WAIT_L(0); PG8_BAR; PG8_MMA(1, 0, At, B0); PG8_MMA(1, 1, At, B1); PG8_BAR; PG8_SCHED;
.LBB0_577:
	ds_read_b128 v[128:131], v212
	ds_read_b128 v[132:135], v212 offset:1024
	ds_read_b128 v[136:139], v212 offset:2048
	ds_read_b128 v[140:143], v212 offset:3072
	ds_read_b128 v[144:147], v213
	ds_read_b128 v[148:151], v213 offset:1024
	ds_read_b128 v[152:155], v213 offset:2048
	ds_read_b128 v[156:159], v213 offset:3072
	s_add_u32 s8, s6, 0xfff00080
	s_addc_u32 s9, s7, -1
	s_cmp_eq_u32 s43, 60
	s_cselect_b32 s41, s1, s9
	s_cselect_b32 s40, s2, s8
	s_cselect_b32 s9, s5, s42
	s_cselect_b32 s8, s29, s31
	v_lshl_add_u64 v[204:205], s[6:7], 0, v[178:179]
	s_add_i32 m0, s48, 0xc000
	ds_read_b128 v[160:163], v214
	ds_read_b128 v[184:187], v214 offset:1024
	ds_read_b128 v[188:191], v214 offset:2048
	ds_read_b128 v[192:195], v214 offset:3072
	ds_read_b128 v[196:199], v214 offset:4096
	ds_read_b128 v[200:203], v214 offset:5120
	ds_read_b128 v[216:219], v214 offset:6144
	ds_read_b128 v[220:223], v214 offset:7168
	global_load_lds_dwordx4 v[204:205], off
	v_lshl_add_u64 v[204:205], s[6:7], 0, v[180:181]
	s_add_i32 m0, s48, 0xe000
	s_nop 0
	global_load_lds_dwordx4 v[204:205], off
	s_cmp_lg_u64 s[22:23], 0
	s_cbranch_scc1 .Llw_3
	s_waitcnt vmcnt(8)
.Llw_3:
	s_waitcnt lgkmcnt(0)
	s_barrier
	s_setprio 1
	s_waitcnt lgkmcnt(0)
	v_mfma_f32_16x16x32_bf16 v[124:127], v[128:131], v[160:163], v[124:127]
	v_mfma_f32_16x16x32_bf16 v[120:123], v[136:139], v[160:163], v[120:123]
	v_mfma_f32_16x16x32_bf16 v[108:111], v[128:131], v[188:191], v[108:111]
	v_mfma_f32_16x16x32_bf16 v[104:107], v[136:139], v[188:191], v[104:107]
	v_mfma_f32_16x16x32_bf16 v[92:95], v[128:131], v[196:199], v[92:95]
	v_mfma_f32_16x16x32_bf16 v[88:91], v[136:139], v[196:199], v[88:91]
	v_mfma_f32_16x16x32_bf16 v[76:79], v[128:131], v[216:219], v[76:79]
	v_mfma_f32_16x16x32_bf16 v[72:75], v[136:139], v[216:219], v[72:75]
	v_mfma_f32_16x16x32_bf16 v[124:127], v[132:135], v[184:187], v[124:127]
	v_mfma_f32_16x16x32_bf16 v[120:123], v[140:143], v[184:187], v[120:123]
	v_mfma_f32_16x16x32_bf16 v[108:111], v[132:135], v[192:195], v[108:111]
	v_mfma_f32_16x16x32_bf16 v[104:107], v[140:143], v[192:195], v[104:107]
	v_mfma_f32_16x16x32_bf16 v[92:95], v[132:135], v[200:203], v[92:95]
	v_mfma_f32_16x16x32_bf16 v[88:91], v[140:143], v[200:203], v[88:91]
	v_mfma_f32_16x16x32_bf16 v[76:79], v[132:135], v[220:223], v[76:79]
	v_mfma_f32_16x16x32_bf16 v[72:75], v[140:143], v[220:223], v[72:75]
	s_setprio 0
	s_setprio 1
	v_mfma_f32_16x16x32_bf16 v[116:119], v[144:147], v[160:163], v[116:119]
	v_mfma_f32_16x16x32_bf16 v[112:115], v[152:155], v[160:163], v[112:115]
	v_mfma_f32_16x16x32_bf16 v[100:103], v[144:147], v[188:191], v[100:103]
	v_mfma_f32_16x16x32_bf16 v[96:99], v[152:155], v[188:191], v[96:99]
	v_mfma_f32_16x16x32_bf16 v[84:87], v[144:147], v[196:199], v[84:87]
	v_mfma_f32_16x16x32_bf16 v[80:83], v[152:155], v[196:199], v[80:83]
	v_mfma_f32_16x16x32_bf16 v[68:71], v[144:147], v[216:219], v[68:71]
	v_mfma_f32_16x16x32_bf16 v[64:67], v[152:155], v[216:219], v[64:67]
	v_mfma_f32_16x16x32_bf16 v[116:119], v[148:151], v[184:187], v[116:119]
	v_mfma_f32_16x16x32_bf16 v[112:115], v[156:159], v[184:187], v[112:115]
	v_mfma_f32_16x16x32_bf16 v[100:103], v[148:151], v[192:195], v[100:103]
	v_mfma_f32_16x16x32_bf16 v[96:99], v[156:159], v[192:195], v[96:99]
	v_mfma_f32_16x16x32_bf16 v[84:87], v[148:151], v[200:203], v[84:87]
	v_mfma_f32_16x16x32_bf16 v[80:83], v[156:159], v[200:203], v[80:83]
	v_mfma_f32_16x16x32_bf16 v[68:71], v[148:151], v[220:223], v[68:71]
	v_mfma_f32_16x16x32_bf16 v[64:67], v[156:159], v[220:223], v[64:67]
	s_setprio 0
	s_waitcnt vmcnt(8)
	s_barrier
	s_add_i32 s69, s62, s47
	v_lshl_add_u64 v[204:205], s[8:9], 0, v[166:167]
	s_mov_b32 m0, s69
	ds_read_b128 v[160:163], v214 offset:16384
	ds_read_b128 v[184:187], v214 offset:17408
	ds_read_b128 v[188:191], v214 offset:18432
	ds_read_b128 v[192:195], v214 offset:19456
	ds_read_b128 v[196:199], v214 offset:20480
	ds_read_b128 v[200:203], v214 offset:21504
	ds_read_b128 v[216:219], v214 offset:22528
	ds_read_b128 v[220:223], v214 offset:23552
	global_load_lds_dwordx4 v[204:205], off
	s_add_i32 m0, s69, 0x2000
	s_add_u32 s70, s8, 0x100000
	v_lshl_add_u64 v[224:225], s[8:9], 0, v[170:171]
	s_addc_u32 s71, s9, 0
	s_add_i32 s69, s63, s47
	global_load_lds_dwordx4 v[224:225], off
	v_lshl_add_u64 v[226:227], s[70:71], 0, v[166:167]
	s_mov_b32 m0, s69
	v_lshl_add_u64 v[228:229], s[40:41], 0, v[168:169]
	global_load_lds_dwordx4 v[226:227], off
	v_lshl_add_u64 v[226:227], s[70:71], 0, v[170:171]
	s_add_i32 m0, s69, 0x2000
	s_nop 0
	global_load_lds_dwordx4 v[226:227], off
	v_lshl_add_u64 v[226:227], s[40:41], 0, v[164:165]
	s_mov_b32 m0, s48
	s_nop 0
	global_load_lds_dwordx4 v[226:227], off
	s_mov_b32 m0, s49
	s_nop 0
	global_load_lds_dwordx4 v[228:229], off
	s_cmp_lg_u64 s[22:23], 0
	s_cbranch_scc1 .Llw_2
	s_waitcnt vmcnt(8)
; #define PG8_STAGE(bufoff, gbase, voff) do { _Pragma("unroll") for (int _i = 0; _i < 2; ++_i) \
;         __builtin_amdgcn_global_load_lds((const unsigned*)((const char*)(gbase) + (voff)[_i]), (PG8_LAS unsigned*)(lds + (bufoff) + ldsw + _i * 8192), 16, 0, 0); } while (0)
; #define PG8_LDA(dst, b, h) do { _Pragma("unroll") for (int m = 0; m < 4; ++m) _Pragma("unroll") for (int k = 0; k < 2; ++k) dst[m][k] = *(const PG8_LAS bf16x8*)(lds + PG8_SA(b, h) + aoff + m * 2048 + k * 1024); } while (0)
; #define PG8_LDB(dst, b, h) do { _Pragma("unroll") for (int n = 0; n < 2; ++n) _Pragma("unroll") for (int k = 0; k < 2; ++k) dst[n][k] = *(const PG8_LAS bf16x8*)(lds + PG8_SB(b, h) + boff + n * 2048 + k * 1024); } while (0)
; #define PG8_MMA(ai, bj, At, Bt) do { __builtin_amdgcn_s_setprio(1); _Pragma("unroll") for (int m = 0; m < 4; ++m) _Pragma("unroll") for (int n = 0; n < 2; ++n) _Pragma("unroll") for (int k = 0; k < 2; ++k) \
;         acc[ai][bj][m][n] = __builtin_amdgcn_mfma_f32_16x16x32_bf16(Bt[n][k], At[m][k], acc[ai][bj][m][n], 0, 0, 0); __builtin_amdgcn_s_setprio(0); } while (0)
; #define PG8_WAIT_V(n) asm volatile("s_waitcnt vmcnt(" #n ")" ::: "memory")
; #define PG8_WAIT_L(n) asm volatile("s_waitcnt lgkmcnt(" #n ")" ::: "memory")
; #define PG8_BAR __builtin_amdgcn_s_barrier()
; #define PG8_SCHED __builtin_amdgcn_sched_barrier(0)
; template <class Epi, class Sched, bool ALIGN_EPI = false, bool SP2 = false>
; __device__ __forceinline__ void gemm_phase(PG8_LAS unsigned char* lds, const Gemm g, const Sched& S, const Epi& E, int tid_in) {
;     ...
;             PG8_WAIT_V(8); PG8_WAIT_L(0); PG8_BAR; PG8_MMA(1, 0, At, B0); PG8_MMA(1, 1, At, B1); PG8_BAR; PG8_SCHED;
;             PG8_LDB(B0, 1, 0); PG8_LDB(B1, 1, 1); PG8_SCHED; PG8_LDA(At, 1, 0); PG8_STAGE(PG8_SA(0, 1), a2 + hstep, voffA);
;             PG8_WAIT_V(8); PG8_WAIT_L(0); PG8_BAR; PG8_MMA(0, 0, At, B0); PG8_MMA(0, 1, At, B1); PG8_BAR; PG8_SCHED;
.Llw_2:
	s_waitcnt lgkmcnt(0)
	s_barrier
	s_setprio 1
	s_waitcnt lgkmcnt(0)
	v_mfma_f32_16x16x32_bf16 v[60:63], v[128:131], v[160:163], v[60:63]
	v_mfma_f32_16x16x32_bf16 v[56:59], v[136:139], v[160:163], v[56:59]
	v_mfma_f32_16x16x32_bf16 v[44:47], v[128:131], v[188:191], v[44:47]
	v_mfma_f32_16x16x32_bf16 v[40:43], v[136:139], v[188:191], v[40:43]
	v_mfma_f32_16x16x32_bf16 v[28:31], v[128:131], v[196:199], v[28:31]
	v_mfma_f32_16x16x32_bf16 v[24:27], v[136:139], v[196:199], v[24:27]
	v_mfma_f32_16x16x32_bf16 v[12:15], v[128:131], v[216:219], v[12:15]
	v_mfma_f32_16x16x32_bf16 v[8:11], v[136:139], v[216:219], v[8:11]
	v_mfma_f32_16x16x32_bf16 v[60:63], v[132:135], v[184:187], v[60:63]
	v_mfma_f32_16x16x32_bf16 v[56:59], v[140:143], v[184:187], v[56:59]
	v_mfma_f32_16x16x32_bf16 v[44:47], v[132:135], v[192:195], v[44:47]
	v_mfma_f32_16x16x32_bf16 v[40:43], v[140:143], v[192:195], v[40:43]
	v_mfma_f32_16x16x32_bf16 v[28:31], v[132:135], v[200:203], v[28:31]
	v_mfma_f32_16x16x32_bf16 v[24:27], v[140:143], v[200:203], v[24:27]
	v_mfma_f32_16x16x32_bf16 v[12:15], v[132:135], v[220:223], v[12:15]
	v_mfma_f32_16x16x32_bf16 v[8:11], v[140:143], v[220:223], v[8:11]
	s_setprio 0
	s_setprio 1
	v_mfma_f32_16x16x32_bf16 v[52:55], v[144:147], v[160:163], v[52:55]
	v_mfma_f32_16x16x32_bf16 v[48:51], v[152:155], v[160:163], v[48:51]
	v_mfma_f32_16x16x32_bf16 v[36:39], v[144:147], v[188:191], v[36:39]
	v_mfma_f32_16x16x32_bf16 v[32:35], v[152:155], v[188:191], v[32:35]
	v_mfma_f32_16x16x32_bf16 v[20:23], v[144:147], v[196:199], v[20:23]
	v_mfma_f32_16x16x32_bf16 v[16:19], v[152:155], v[196:199], v[16:19]
	v_mfma_f32_16x16x32_bf16 v[4:7], v[144:147], v[216:219], v[4:7]
	v_mfma_f32_16x16x32_bf16 v[0:3], v[152:155], v[216:219], v[0:3]
	v_mfma_f32_16x16x32_bf16 v[52:55], v[148:151], v[184:187], v[52:55]
	v_mfma_f32_16x16x32_bf16 v[48:51], v[156:159], v[184:187], v[48:51]
	v_mfma_f32_16x16x32_bf16 v[36:39], v[148:151], v[192:195], v[36:39]
	v_mfma_f32_16x16x32_bf16 v[32:35], v[156:159], v[192:195], v[32:35]
	v_mfma_f32_16x16x32_bf16 v[20:23], v[148:151], v[200:203], v[20:23]
	v_mfma_f32_16x16x32_bf16 v[16:19], v[156:159], v[200:203], v[16:19]
	v_mfma_f32_16x16x32_bf16 v[4:7], v[148:151], v[220:223], v[4:7]
	v_mfma_f32_16x16x32_bf16 v[0:3], v[156:159], v[220:223], v[0:3]
	s_setprio 0
	s_waitcnt vmcnt(8)
	s_barrier
	s_add_i32 s69, 0, 0x18000
	s_add_i32 s70, 0, 0x1c000
	v_add_u32_e32 v140, s69, v207
	v_add_u32_e32 v156, s70, v207
	ds_read_b128 v[128:131], v140
	ds_read_b128 v[132:135], v140 offset:1024
	ds_read_b128 v[136:139], v140 offset:2048
	ds_read_b128 v[140:143], v140 offset:3072
	ds_read_b128 v[144:147], v156
	ds_read_b128 v[148:151], v156 offset:1024
	ds_read_b128 v[152:155], v156 offset:2048
	ds_read_b128 v[156:159], v156 offset:3072
	s_add_u32 s40, s40, 0x100000
	s_addc_u32 s41, s41, 0
	s_mov_b32 m0, s50
	v_lshl_add_u64 v[230:231], s[40:41], 0, v[164:165]
	ds_read_b128 v[160:163], v214 offset:32768
	ds_read_b128 v[184:187], v214 offset:33792
	ds_read_b128 v[188:191], v214 offset:34816
	ds_read_b128 v[192:195], v214 offset:35840
	ds_read_b128 v[196:199], v214 offset:36864
	ds_read_b128 v[200:203], v214 offset:37888
	ds_read_b128 v[216:219], v214 offset:38912
	ds_read_b128 v[220:223], v214 offset:39936
	global_load_lds_dwordx4 v[230:231], off
	v_lshl_add_u64 v[230:231], s[40:41], 0, v[168:169]
	s_mov_b32 m0, s51
	s_nop 0
	global_load_lds_dwordx4 v[230:231], off
	s_cmp_lg_u64 s[22:23], 0
	s_cbranch_scc1 .Llw_1
	s_waitcnt vmcnt(8)
; #define PG8_STAGE(bufoff, gbase, voff) do { _Pragma("unroll") for (int _i = 0; _i < 2; ++_i) \
;         __builtin_amdgcn_global_load_lds((const unsigned*)((const char*)(gbase) + (voff)[_i]), (PG8_LAS unsigned*)(lds + (bufoff) + ldsw + _i * 8192), 16, 0, 0); } while (0)
; #define PG8_LDA(dst, b, h) do { _Pragma("unroll") for (int m = 0; m < 4; ++m) _Pragma("unroll") for (int k = 0; k < 2; ++k) dst[m][k] = *(const PG8_LAS bf16x8*)(lds + PG8_SA(b, h) + aoff + m * 2048 + k * 1024); } while (0)
; #define PG8_MMA(ai, bj, At, Bt) do { __builtin_amdgcn_s_setprio(1); _Pragma("unroll") for (int m = 0; m < 4; ++m) _Pragma("unroll") for (int n = 0; n < 2; ++n) _Pragma("unroll") for (int k = 0; k < 2; ++k) \
;         acc[ai][bj][m][n] = __builtin_amdgcn_mfma_f32_16x16x32_bf16(Bt[n][k], At[m][k], acc[ai][bj][m][n], 0, 0, 0); __builtin_amdgcn_s_setprio(0); } while (0)
; #define PG8_WAIT_V(n) asm volatile("s_waitcnt vmcnt(" #n ")" ::: "memory")
; #define PG8_WAIT_L(n) asm volatile("s_waitcnt lgkmcnt(" #n ")" ::: "memory")
; #define PG8_BAR __builtin_amdgcn_s_barrier()
; #define PG8_SCHED __builtin_amdgcn_sched_barrier(0)
; template <class Epi, class Sched, bool ALIGN_EPI = false, bool SP2 = false>
; __device__ __forceinline__ void gemm_phase(PG8_LAS unsigned char* lds, const Gemm g, const Sched& S, const Epi& E, int tid_in) {
;     ...
;             PG8_WAIT_V(8); PG8_WAIT_L(0); PG8_BAR; PG8_MMA(0, 0, At, B0); PG8_MMA(0, 1, At, B1); PG8_BAR; PG8_SCHED;
;             PG8_LDA(At, 1, 1); PG8_STAGE(PG8_SB(1, 0), b3, voffB); PG8_STAGE(PG8_SB(1, 1), b3 + hstep, voffB); PG8_STAGE(PG8_SA(1, 0), a3, voffA);
;             PG8_WAIT_V(8); PG8_WAIT_L(0); PG8_BAR; PG8_MMA(1, 0, At, B0); PG8_MMA(1, 1, At, B1); PG8_BAR; PG8_SCHED;
.Llw_1:
	s_waitcnt lgkmcnt(0)
	s_barrier
	s_setprio 1
	s_waitcnt lgkmcnt(0)
	v_mfma_f32_16x16x32_bf16 v[124:127], v[128:131], v[160:163], v[124:127]
	v_mfma_f32_16x16x32_bf16 v[120:123], v[136:139], v[160:163], v[120:123]
	v_mfma_f32_16x16x32_bf16 v[108:111], v[128:131], v[188:191], v[108:111]
	v_mfma_f32_16x16x32_bf16 v[104:107], v[136:139], v[188:191], v[104:107]
	v_mfma_f32_16x16x32_bf16 v[92:95], v[128:131], v[196:199], v[92:95]
	v_mfma_f32_16x16x32_bf16 v[88:91], v[136:139], v[196:199], v[88:91]
	v_mfma_f32_16x16x32_bf16 v[76:79], v[128:131], v[216:219], v[76:79]
	v_mfma_f32_16x16x32_bf16 v[72:75], v[136:139], v[216:219], v[72:75]
	v_mfma_f32_16x16x32_bf16 v[124:127], v[132:135], v[184:187], v[124:127]
	v_mfma_f32_16x16x32_bf16 v[120:123], v[140:143], v[184:187], v[120:123]
	v_mfma_f32_16x16x32_bf16 v[108:111], v[132:135], v[192:195], v[108:111]
	v_mfma_f32_16x16x32_bf16 v[104:107], v[140:143], v[192:195], v[104:107]
	v_mfma_f32_16x16x32_bf16 v[92:95], v[132:135], v[200:203], v[92:95]
	v_mfma_f32_16x16x32_bf16 v[88:91], v[140:143], v[200:203], v[88:91]
	v_mfma_f32_16x16x32_bf16 v[76:79], v[132:135], v[220:223], v[76:79]
	v_mfma_f32_16x16x32_bf16 v[72:75], v[140:143], v[220:223], v[72:75]
	s_setprio 0
	s_setprio 1
	v_mfma_f32_16x16x32_bf16 v[116:119], v[144:147], v[160:163], v[116:119]
	v_mfma_f32_16x16x32_bf16 v[112:115], v[152:155], v[160:163], v[112:115]
	v_mfma_f32_16x16x32_bf16 v[100:103], v[144:147], v[188:191], v[100:103]
	v_mfma_f32_16x16x32_bf16 v[96:99], v[152:155], v[188:191], v[96:99]
	v_mfma_f32_16x16x32_bf16 v[84:87], v[144:147], v[196:199], v[84:87]
	v_mfma_f32_16x16x32_bf16 v[80:83], v[152:155], v[196:199], v[80:83]
	v_mfma_f32_16x16x32_bf16 v[68:71], v[144:147], v[216:219], v[68:71]
	v_mfma_f32_16x16x32_bf16 v[64:67], v[152:155], v[216:219], v[64:67]
	v_mfma_f32_16x16x32_bf16 v[116:119], v[148:151], v[184:187], v[116:119]
	v_mfma_f32_16x16x32_bf16 v[112:115], v[156:159], v[184:187], v[112:115]
	v_mfma_f32_16x16x32_bf16 v[100:103], v[148:151], v[192:195], v[100:103]
	v_mfma_f32_16x16x32_bf16 v[96:99], v[156:159], v[192:195], v[96:99]
	v_mfma_f32_16x16x32_bf16 v[84:87], v[148:151], v[200:203], v[84:87]
	v_mfma_f32_16x16x32_bf16 v[80:83], v[156:159], v[200:203], v[80:83]
	v_mfma_f32_16x16x32_bf16 v[68:71], v[148:151], v[220:223], v[68:71]
	v_mfma_f32_16x16x32_bf16 v[64:67], v[156:159], v[220:223], v[64:67]
	s_setprio 0
	s_waitcnt vmcnt(8)
	s_barrier
	s_add_i32 s40, s69, s47
	v_lshl_add_u64 v[204:205], v[204:205], 0, s[20:21]
	s_mov_b32 m0, s40
	ds_read_b128 v[160:163], v214 offset:49152
	ds_read_b128 v[184:187], v214 offset:50176
	ds_read_b128 v[188:191], v214 offset:51200
	ds_read_b128 v[192:195], v214 offset:52224
	ds_read_b128 v[196:199], v214 offset:53248
	ds_read_b128 v[200:203], v214 offset:54272
	ds_read_b128 v[216:219], v214 offset:55296
	ds_read_b128 v[220:223], v214 offset:56320
	global_load_lds_dwordx4 v[204:205], off
	s_add_i32 m0, s40, 0x2000
	s_add_u32 s8, s8, 0x100080
	v_lshl_add_u64 v[204:205], v[224:225], 0, s[20:21]
	s_addc_u32 s9, s9, 0
	s_add_i32 s40, s70, s47
	global_load_lds_dwordx4 v[204:205], off
	v_lshl_add_u64 v[204:205], s[8:9], 0, v[166:167]
	s_mov_b32 m0, s40
	s_nop 0
	global_load_lds_dwordx4 v[204:205], off
	v_lshl_add_u64 v[204:205], s[8:9], 0, v[170:171]
	s_add_i32 m0, s40, 0x2000
	s_nop 0
	global_load_lds_dwordx4 v[204:205], off
	v_lshl_add_u64 v[204:205], v[226:227], 0, s[20:21]
	s_mov_b32 m0, s58
	s_nop 0
	global_load_lds_dwordx4 v[204:205], off
	v_lshl_add_u64 v[204:205], v[228:229], 0, s[20:21]
	s_mov_b32 m0, s59
	s_nop 0
	global_load_lds_dwordx4 v[204:205], off
	s_cmp_lg_u64 s[22:23], 0
	s_cbranch_scc1 .Llw_0
	s_waitcnt vmcnt(8)
.Llw_0:
	s_waitcnt lgkmcnt(0)
	s_barrier
	s_setprio 1
	s_waitcnt lgkmcnt(0)
	v_mfma_f32_16x16x32_bf16 v[60:63], v[128:131], v[160:163], v[60:63]
	v_mfma_f32_16x16x32_bf16 v[56:59], v[136:139], v[160:163], v[56:59]
	v_mfma_f32_16x16x32_bf16 v[44:47], v[128:131], v[188:191], v[44:47]
	v_mfma_f32_16x16x32_bf16 v[40:43], v[136:139], v[188:191], v[40:43]
	v_mfma_f32_16x16x32_bf16 v[28:31], v[128:131], v[196:199], v[28:31]
	v_mfma_f32_16x16x32_bf16 v[24:27], v[136:139], v[196:199], v[24:27]
	v_mfma_f32_16x16x32_bf16 v[12:15], v[128:131], v[216:219], v[12:15]
	v_mfma_f32_16x16x32_bf16 v[8:11], v[136:139], v[216:219], v[8:11]
	v_mfma_f32_16x16x32_bf16 v[60:63], v[132:135], v[184:187], v[60:63]
	v_mfma_f32_16x16x32_bf16 v[56:59], v[140:143], v[184:187], v[56:59]
	v_mfma_f32_16x16x32_bf16 v[44:47], v[132:135], v[192:195], v[44:47]
	v_mfma_f32_16x16x32_bf16 v[40:43], v[140:143], v[192:195], v[40:43]
	v_mfma_f32_16x16x32_bf16 v[28:31], v[132:135], v[200:203], v[28:31]
	v_mfma_f32_16x16x32_bf16 v[24:27], v[140:143], v[200:203], v[24:27]
	v_mfma_f32_16x16x32_bf16 v[12:15], v[132:135], v[220:223], v[12:15]
	v_mfma_f32_16x16x32_bf16 v[8:11], v[140:143], v[220:223], v[8:11]
	s_setprio 0
	s_setprio 1
	v_mfma_f32_16x16x32_bf16 v[52:55], v[144:147], v[160:163], v[52:55]
	v_mfma_f32_16x16x32_bf16 v[48:51], v[152:155], v[160:163], v[48:51]
	v_mfma_f32_16x16x32_bf16 v[36:39], v[144:147], v[188:191], v[36:39]
	v_mfma_f32_16x16x32_bf16 v[32:35], v[152:155], v[188:191], v[32:35]
	v_mfma_f32_16x16x32_bf16 v[20:23], v[144:147], v[196:199], v[20:23]
	v_mfma_f32_16x16x32_bf16 v[16:19], v[152:155], v[196:199], v[16:19]
	v_mfma_f32_16x16x32_bf16 v[4:7], v[144:147], v[216:219], v[4:7]
	v_mfma_f32_16x16x32_bf16 v[0:3], v[152:155], v[216:219], v[0:3]
	v_mfma_f32_16x16x32_bf16 v[52:55], v[148:151], v[184:187], v[52:55]
	v_mfma_f32_16x16x32_bf16 v[48:51], v[156:159], v[184:187], v[48:51]
	v_mfma_f32_16x16x32_bf16 v[36:39], v[148:151], v[192:195], v[36:39]
	v_mfma_f32_16x16x32_bf16 v[32:35], v[156:159], v[192:195], v[32:35]
	v_mfma_f32_16x16x32_bf16 v[20:23], v[148:151], v[200:203], v[20:23]
	v_mfma_f32_16x16x32_bf16 v[16:19], v[156:159], v[200:203], v[16:19]
	v_mfma_f32_16x16x32_bf16 v[4:7], v[148:151], v[220:223], v[4:7]
	v_mfma_f32_16x16x32_bf16 v[0:3], v[156:159], v[220:223], v[0:3]
	s_setprio 0
	s_waitcnt vmcnt(8)
	s_barrier
	s_add_i32 s43, s43, 2
	s_add_u32 s6, s6, 0x100
	s_addc_u32 s7, s7, 0
	s_add_u32 s31, s31, 0x100
	s_addc_u32 s42, s42, 0
	s_cmp_gt_u32 s43, 61
	s_cbranch_scc0 .LBB0_577
	s_and_b64 vcc, exec, s[22:23]
	s_cbranch_vccnz .LBB0_581
	v_lshl_add_u32 v184, s4, 8, v206
	s_cmp_gt_i32 s0, 15
	s_mov_b64 s[4:5], -1
	s_cbranch_scc1 .LBB0_582

; #define PG8_STAGE(bufoff, gbase, voff) do { _Pragma("unroll") for (int _i = 0; _i < 2; ++_i) \
;         __builtin_amdgcn_global_load_lds((const unsigned*)((const char*)(gbase) + (voff)[_i]), (PG8_LAS unsigned*)(lds + (bufoff) + ldsw + _i * 8192), 16, 0, 0); } while (0)
; #define PG8_LDA(dst, b, h) do { _Pragma("unroll") for (int m = 0; m < 4; ++m) _Pragma("unroll") for (int k = 0; k < 2; ++k) dst[m][k] = *(const PG8_LAS bf16x8*)(lds + PG8_SA(b, h) + aoff + m * 2048 + k * 1024); } while (0)
; #define PG8_LDB(dst, b, h) do { _Pragma("unroll") for (int n = 0; n < 2; ++n) _Pragma("unroll") for (int k = 0; k < 2; ++k) dst[n][k] = *(const PG8_LAS bf16x8*)(lds + PG8_SB(b, h) + boff + n * 2048 + k * 1024); } while (0)
; #define PG8_MMA(ai, bj, At, Bt) do { __builtin_amdgcn_s_setprio(1); _Pragma("unroll") for (int m = 0; m < 4; ++m) _Pragma("unroll") for (int n = 0; n < 2; ++n) _Pragma("unroll") for (int k = 0; k < 2; ++k) \
;         acc[ai][bj][m][n] = __builtin_amdgcn_mfma_f32_16x16x32_bf16(Bt[n][k], At[m][k], acc[ai][bj][m][n], 0, 0, 0); __builtin_amdgcn_s_setprio(0); } while (0)
; #define PG8_WAIT_V(n) asm volatile("s_waitcnt vmcnt(" #n ")" ::: "memory")
; #define PG8_WAIT_L(n) asm volatile("s_waitcnt lgkmcnt(" #n ")" ::: "memory")
; #define PG8_BAR __builtin_amdgcn_s_barrier()
; #define PG8_SCHED __builtin_amdgcn_sched_barrier(0)
; template <class Epi, class Sched, bool ALIGN_EPI = false, bool SP2 = false>
; __device__ __forceinline__ void gemm_phase(PG8_LAS unsigned char* lds, const Gemm g, const Sched& S, const Epi& E, int tid_in) {
;     ...
;             PG8_LDB(B0, 0, 0); PG8_LDB(B1, 0, 1); PG8_SCHED; PG8_LDA(At, 0, 0); PG8_STAGE(PG8_SA(1, 1), a1 + hstep, voffA);
;             PG8_WAIT_V(8); PG8_WAIT_L(0); PG8_BAR; PG8_MMA(0, 0, At, B0); PG8_MMA(0, 1, At, B1); PG8_BAR; PG8_SCHED;
;             PG8_LDA(At, 0, 1); PG8_STAGE(PG8_SB(0, 0), b2, voffB); PG8_STAGE(PG8_SB(0, 1), b2 + hstep, voffB); PG8_STAGE(PG8_SA(0, 0), a2, voffA);
;             PG8_WAIT_V(8); PG8_WAIT_L(0); PG8_BAR; PG8_MMA(1, 0, At, B0); PG8_MMA(1, 1, At, B1); PG8_BAR; PG8_SCHED;
.LBB0_1369:
	ds_read_b128 v[144:147], v153
	ds_read_b128 v[156:159], v153 offset:1024
	ds_read_b128 v[160:163], v153 offset:2048
	ds_read_b128 v[164:167], v153 offset:3072
	ds_read_b128 v[168:171], v154
	ds_read_b128 v[172:175], v154 offset:1024
	ds_read_b128 v[176:179], v154 offset:2048
	ds_read_b128 v[180:183], v154 offset:3072
	s_add_u32 s28, s26, 0xfff00080
	s_addc_u32 s29, s27, -1
	s_cmp_eq_u32 s54, 60
	s_cselect_b32 s31, s2, s29
	s_cselect_b32 s30, s15, s28
	s_cselect_b32 s29, s13, s53
	s_cselect_b32 s28, s23, s25
	v_lshl_add_u64 v[148:149], s[26:27], 0, v[138:139]
	s_add_i32 m0, s37, 0xc000
	ds_read_b128 v[184:187], v155
	ds_read_b128 v[188:191], v155 offset:1024
	ds_read_b128 v[192:195], v155 offset:2048
	ds_read_b128 v[196:199], v155 offset:3072
	ds_read_b128 v[200:203], v155 offset:4096
	ds_read_b128 v[204:207], v155 offset:5120
	ds_read_b128 v[208:211], v155 offset:6144
	ds_read_b128 v[212:215], v155 offset:7168
	global_load_lds_dwordx4 v[148:149], off
	v_lshl_add_u64 v[148:149], s[26:27], 0, v[140:141]
	s_add_i32 m0, s37, 0xe000
	s_nop 0
	global_load_lds_dwordx4 v[148:149], off
	s_cmp_lg_u64 s[8:9], 0
	s_cbranch_scc1 .Llw_7
	s_waitcnt vmcnt(8)
.Llw_7:
	s_waitcnt lgkmcnt(0)
	s_barrier
	s_setprio 1
	s_waitcnt lgkmcnt(0)
	v_mfma_f32_16x16x32_bf16 v[124:127], v[144:147], v[184:187], v[124:127]
	v_mfma_f32_16x16x32_bf16 v[120:123], v[160:163], v[184:187], v[120:123]
	v_mfma_f32_16x16x32_bf16 v[108:111], v[144:147], v[192:195], v[108:111]
	v_mfma_f32_16x16x32_bf16 v[104:107], v[160:163], v[192:195], v[104:107]
	v_mfma_f32_16x16x32_bf16 v[92:95], v[144:147], v[200:203], v[92:95]
	v_mfma_f32_16x16x32_bf16 v[88:91], v[160:163], v[200:203], v[88:91]
	v_mfma_f32_16x16x32_bf16 v[76:79], v[144:147], v[208:211], v[76:79]
	v_mfma_f32_16x16x32_bf16 v[72:75], v[160:163], v[208:211], v[72:75]
	v_mfma_f32_16x16x32_bf16 v[124:127], v[156:159], v[188:191], v[124:127]
	v_mfma_f32_16x16x32_bf16 v[120:123], v[164:167], v[188:191], v[120:123]
	v_mfma_f32_16x16x32_bf16 v[108:111], v[156:159], v[196:199], v[108:111]
	v_mfma_f32_16x16x32_bf16 v[104:107], v[164:167], v[196:199], v[104:107]
	v_mfma_f32_16x16x32_bf16 v[92:95], v[156:159], v[204:207], v[92:95]
	v_mfma_f32_16x16x32_bf16 v[88:91], v[164:167], v[204:207], v[88:91]
	v_mfma_f32_16x16x32_bf16 v[76:79], v[156:159], v[212:215], v[76:79]
	v_mfma_f32_16x16x32_bf16 v[72:75], v[164:167], v[212:215], v[72:75]
	s_setprio 0
	s_setprio 1
	v_mfma_f32_16x16x32_bf16 v[116:119], v[168:171], v[184:187], v[116:119]
	v_mfma_f32_16x16x32_bf16 v[112:115], v[176:179], v[184:187], v[112:115]
	v_mfma_f32_16x16x32_bf16 v[100:103], v[168:171], v[192:195], v[100:103]
	v_mfma_f32_16x16x32_bf16 v[96:99], v[176:179], v[192:195], v[96:99]
	v_mfma_f32_16x16x32_bf16 v[84:87], v[168:171], v[200:203], v[84:87]
	v_mfma_f32_16x16x32_bf16 v[80:83], v[176:179], v[200:203], v[80:83]
	v_mfma_f32_16x16x32_bf16 v[68:71], v[168:171], v[208:211], v[68:71]
	v_mfma_f32_16x16x32_bf16 v[64:67], v[176:179], v[208:211], v[64:67]
	v_mfma_f32_16x16x32_bf16 v[116:119], v[172:175], v[188:191], v[116:119]
	v_mfma_f32_16x16x32_bf16 v[112:115], v[180:183], v[188:191], v[112:115]
	v_mfma_f32_16x16x32_bf16 v[100:103], v[172:175], v[196:199], v[100:103]
	v_mfma_f32_16x16x32_bf16 v[96:99], v[180:183], v[196:199], v[96:99]
	v_mfma_f32_16x16x32_bf16 v[84:87], v[172:175], v[204:207], v[84:87]
	v_mfma_f32_16x16x32_bf16 v[80:83], v[180:183], v[204:207], v[80:83]
	v_mfma_f32_16x16x32_bf16 v[68:71], v[172:175], v[212:215], v[68:71]
	v_mfma_f32_16x16x32_bf16 v[64:67], v[180:183], v[212:215], v[64:67]
	s_setprio 0
	s_waitcnt vmcnt(8)
	s_barrier
	s_add_i32 s55, s46, s36
	v_lshl_add_u64 v[148:149], s[28:29], 0, v[130:131]
	s_mov_b32 m0, s55
	ds_read_b128 v[184:187], v155 offset:16384
	ds_read_b128 v[188:191], v155 offset:17408
	ds_read_b128 v[192:195], v155 offset:18432
	ds_read_b128 v[196:199], v155 offset:19456
	ds_read_b128 v[200:203], v155 offset:20480
	ds_read_b128 v[204:207], v155 offset:21504
	ds_read_b128 v[208:211], v155 offset:22528
	ds_read_b128 v[212:215], v155 offset:23552
	global_load_lds_dwordx4 v[148:149], off
	s_add_i32 m0, s55, 0x2000
	s_add_u32 s56, s28, 0x100000
	v_lshl_add_u64 v[216:217], s[28:29], 0, v[134:135]
	s_addc_u32 s57, s29, 0
	s_add_i32 s55, s47, s36
	global_load_lds_dwordx4 v[216:217], off
	v_lshl_add_u64 v[218:219], s[56:57], 0, v[130:131]
	s_mov_b32 m0, s55
	v_lshl_add_u64 v[220:221], s[30:31], 0, v[132:133]
	global_load_lds_dwordx4 v[218:219], off
	v_lshl_add_u64 v[218:219], s[56:57], 0, v[134:135]
	s_add_i32 m0, s55, 0x2000
	s_nop 0
	global_load_lds_dwordx4 v[218:219], off
	v_lshl_add_u64 v[218:219], s[30:31], 0, v[128:129]
	s_mov_b32 m0, s37
	s_nop 0
	global_load_lds_dwordx4 v[218:219], off
	s_mov_b32 m0, s38
	s_nop 0
	global_load_lds_dwordx4 v[220:221], off
	s_cmp_lg_u64 s[8:9], 0
	s_cbranch_scc1 .Llw_6
	s_waitcnt vmcnt(8)
; #define PG8_STAGE(bufoff, gbase, voff) do { _Pragma("unroll") for (int _i = 0; _i < 2; ++_i) \
;         __builtin_amdgcn_global_load_lds((const unsigned*)((const char*)(gbase) + (voff)[_i]), (PG8_LAS unsigned*)(lds + (bufoff) + ldsw + _i * 8192), 16, 0, 0); } while (0)
; #define PG8_LDA(dst, b, h) do { _Pragma("unroll") for (int m = 0; m < 4; ++m) _Pragma("unroll") for (int k = 0; k < 2; ++k) dst[m][k] = *(const PG8_LAS bf16x8*)(lds + PG8_SA(b, h) + aoff + m * 2048 + k * 1024); } while (0)
; #define PG8_LDB(dst, b, h) do { _Pragma("unroll") for (int n = 0; n < 2; ++n) _Pragma("unroll") for (int k = 0; k < 2; ++k) dst[n][k] = *(const PG8_LAS bf16x8*)(lds + PG8_SB(b, h) + boff + n * 2048 + k * 1024); } while (0)
; #define PG8_MMA(ai, bj, At, Bt) do { __builtin_amdgcn_s_setprio(1); _Pragma("unroll") for (int m = 0; m < 4; ++m) _Pragma("unroll") for (int n = 0; n < 2; ++n) _Pragma("unroll") for (int k = 0; k < 2; ++k) \
;         acc[ai][bj][m][n] = __builtin_amdgcn_mfma_f32_16x16x32_bf16(Bt[n][k], At[m][k], acc[ai][bj][m][n], 0, 0, 0); __builtin_amdgcn_s_setprio(0); } while (0)
; #define PG8_WAIT_V(n) asm volatile("s_waitcnt vmcnt(" #n ")" ::: "memory")
; #define PG8_WAIT_L(n) asm volatile("s_waitcnt lgkmcnt(" #n ")" ::: "memory")
; #define PG8_BAR __builtin_amdgcn_s_barrier()
; #define PG8_SCHED __builtin_amdgcn_sched_barrier(0)
; template <class Epi, class Sched, bool ALIGN_EPI = false, bool SP2 = false>
; __device__ __forceinline__ void gemm_phase(PG8_LAS unsigned char* lds, const Gemm g, const Sched& S, const Epi& E, int tid_in) {
;     ...
;             PG8_WAIT_V(8); PG8_WAIT_L(0); PG8_BAR; PG8_MMA(1, 0, At, B0); PG8_MMA(1, 1, At, B1); PG8_BAR; PG8_SCHED;
;             PG8_LDB(B0, 1, 0); PG8_LDB(B1, 1, 1); PG8_SCHED; PG8_LDA(At, 1, 0); PG8_STAGE(PG8_SA(0, 1), a2 + hstep, voffA);
;             PG8_WAIT_V(8); PG8_WAIT_L(0); PG8_BAR; PG8_MMA(0, 0, At, B0); PG8_MMA(0, 1, At, B1); PG8_BAR; PG8_SCHED;
.Llw_6:
	s_waitcnt lgkmcnt(0)
	s_barrier
	s_setprio 1
	s_waitcnt lgkmcnt(0)
	v_mfma_f32_16x16x32_bf16 v[60:63], v[144:147], v[184:187], v[60:63]
	v_mfma_f32_16x16x32_bf16 v[56:59], v[160:163], v[184:187], v[56:59]
	v_mfma_f32_16x16x32_bf16 v[44:47], v[144:147], v[192:195], v[44:47]
	v_mfma_f32_16x16x32_bf16 v[40:43], v[160:163], v[192:195], v[40:43]
	v_mfma_f32_16x16x32_bf16 v[28:31], v[144:147], v[200:203], v[28:31]
	v_mfma_f32_16x16x32_bf16 v[24:27], v[160:163], v[200:203], v[24:27]
	v_mfma_f32_16x16x32_bf16 v[12:15], v[144:147], v[208:211], v[12:15]
	v_mfma_f32_16x16x32_bf16 v[8:11], v[160:163], v[208:211], v[8:11]
	v_mfma_f32_16x16x32_bf16 v[60:63], v[156:159], v[188:191], v[60:63]
	v_mfma_f32_16x16x32_bf16 v[56:59], v[164:167], v[188:191], v[56:59]
	v_mfma_f32_16x16x32_bf16 v[44:47], v[156:159], v[196:199], v[44:47]
	v_mfma_f32_16x16x32_bf16 v[40:43], v[164:167], v[196:199], v[40:43]
	v_mfma_f32_16x16x32_bf16 v[28:31], v[156:159], v[204:207], v[28:31]
	v_mfma_f32_16x16x32_bf16 v[24:27], v[164:167], v[204:207], v[24:27]
	v_mfma_f32_16x16x32_bf16 v[12:15], v[156:159], v[212:215], v[12:15]
	v_mfma_f32_16x16x32_bf16 v[8:11], v[164:167], v[212:215], v[8:11]
	s_setprio 0
	s_setprio 1
	v_mfma_f32_16x16x32_bf16 v[52:55], v[168:171], v[184:187], v[52:55]
	v_mfma_f32_16x16x32_bf16 v[48:51], v[176:179], v[184:187], v[48:51]
	v_mfma_f32_16x16x32_bf16 v[36:39], v[168:171], v[192:195], v[36:39]
	v_mfma_f32_16x16x32_bf16 v[32:35], v[176:179], v[192:195], v[32:35]
	v_mfma_f32_16x16x32_bf16 v[20:23], v[168:171], v[200:203], v[20:23]
	v_mfma_f32_16x16x32_bf16 v[16:19], v[176:179], v[200:203], v[16:19]
	v_mfma_f32_16x16x32_bf16 v[4:7], v[168:171], v[208:211], v[4:7]
	v_mfma_f32_16x16x32_bf16 v[0:3], v[176:179], v[208:211], v[0:3]
	v_mfma_f32_16x16x32_bf16 v[52:55], v[172:175], v[188:191], v[52:55]
	v_mfma_f32_16x16x32_bf16 v[48:51], v[180:183], v[188:191], v[48:51]
	v_mfma_f32_16x16x32_bf16 v[36:39], v[172:175], v[196:199], v[36:39]
	v_mfma_f32_16x16x32_bf16 v[32:35], v[180:183], v[196:199], v[32:35]
	v_mfma_f32_16x16x32_bf16 v[20:23], v[172:175], v[204:207], v[20:23]
	v_mfma_f32_16x16x32_bf16 v[16:19], v[180:183], v[204:207], v[16:19]
	v_mfma_f32_16x16x32_bf16 v[4:7], v[172:175], v[212:215], v[4:7]
	v_mfma_f32_16x16x32_bf16 v[0:3], v[180:183], v[212:215], v[0:3]
	s_setprio 0
	s_waitcnt vmcnt(8)
	s_barrier
	s_add_i32 s55, 0, 0x18000
	v_add_u32_e32 v136, s55, v151
	s_add_i32 s56, 0, 0x1c000
	ds_read_b128 v[144:147], v136
	ds_read_b128 v[156:159], v136 offset:1024
	ds_read_b128 v[160:163], v136 offset:2048
	ds_read_b128 v[164:167], v136 offset:3072
	v_add_u32_e32 v136, s56, v151
	ds_read_b128 v[168:171], v136
	ds_read_b128 v[172:175], v136 offset:1024
	ds_read_b128 v[176:179], v136 offset:2048
	ds_read_b128 v[180:183], v136 offset:3072
	s_add_u32 s30, s30, 0x100000
	s_addc_u32 s31, s31, 0
	s_mov_b32 m0, s39
	v_lshl_add_u64 v[222:223], s[30:31], 0, v[128:129]
	ds_read_b128 v[184:187], v155 offset:32768
	ds_read_b128 v[188:191], v155 offset:33792
	ds_read_b128 v[192:195], v155 offset:34816
	ds_read_b128 v[196:199], v155 offset:35840
	ds_read_b128 v[200:203], v155 offset:36864
	ds_read_b128 v[204:207], v155 offset:37888
	ds_read_b128 v[208:211], v155 offset:38912
	ds_read_b128 v[212:215], v155 offset:39936
	global_load_lds_dwordx4 v[222:223], off
	v_lshl_add_u64 v[222:223], s[30:31], 0, v[132:133]
	s_mov_b32 m0, s40
	s_nop 0
	global_load_lds_dwordx4 v[222:223], off
	s_cmp_lg_u64 s[8:9], 0
	s_cbranch_scc1 .Llw_5
	s_waitcnt vmcnt(8)
; #define PG8_STAGE(bufoff, gbase, voff) do { _Pragma("unroll") for (int _i = 0; _i < 2; ++_i) \
;         __builtin_amdgcn_global_load_lds((const unsigned*)((const char*)(gbase) + (voff)[_i]), (PG8_LAS unsigned*)(lds + (bufoff) + ldsw + _i * 8192), 16, 0, 0); } while (0)
; #define PG8_LDA(dst, b, h) do { _Pragma("unroll") for (int m = 0; m < 4; ++m) _Pragma("unroll") for (int k = 0; k < 2; ++k) dst[m][k] = *(const PG8_LAS bf16x8*)(lds + PG8_SA(b, h) + aoff + m * 2048 + k * 1024); } while (0)
; #define PG8_MMA(ai, bj, At, Bt) do { __builtin_amdgcn_s_setprio(1); _Pragma("unroll") for (int m = 0; m < 4; ++m) _Pragma("unroll") for (int n = 0; n < 2; ++n) _Pragma("unroll") for (int k = 0; k < 2; ++k) \
;         acc[ai][bj][m][n] = __builtin_amdgcn_mfma_f32_16x16x32_bf16(Bt[n][k], At[m][k], acc[ai][bj][m][n], 0, 0, 0); __builtin_amdgcn_s_setprio(0); } while (0)
; #define PG8_WAIT_V(n) asm volatile("s_waitcnt vmcnt(" #n ")" ::: "memory")
; #define PG8_WAIT_L(n) asm volatile("s_waitcnt lgkmcnt(" #n ")" ::: "memory")
; #define PG8_BAR __builtin_amdgcn_s_barrier()
; #define PG8_SCHED __builtin_amdgcn_sched_barrier(0)
; template <class Epi, class Sched, bool ALIGN_EPI = false, bool SP2 = false>
; __device__ __forceinline__ void gemm_phase(PG8_LAS unsigned char* lds, const Gemm g, const Sched& S, const Epi& E, int tid_in) {
;     ...
;             PG8_WAIT_V(8); PG8_WAIT_L(0); PG8_BAR; PG8_MMA(0, 0, At, B0); PG8_MMA(0, 1, At, B1); PG8_BAR; PG8_SCHED;
;             PG8_LDA(At, 1, 1); PG8_STAGE(PG8_SB(1, 0), b3, voffB); PG8_STAGE(PG8_SB(1, 1), b3 + hstep, voffB); PG8_STAGE(PG8_SA(1, 0), a3, voffA);
;             PG8_WAIT_V(8); PG8_WAIT_L(0); PG8_BAR; PG8_MMA(1, 0, At, B0); PG8_MMA(1, 1, At, B1); PG8_BAR; PG8_SCHED;
.Llw_5:
	s_waitcnt lgkmcnt(0)
	s_barrier
	s_setprio 1
	s_waitcnt lgkmcnt(0)
	v_mfma_f32_16x16x32_bf16 v[124:127], v[144:147], v[184:187], v[124:127]
	v_mfma_f32_16x16x32_bf16 v[120:123], v[160:163], v[184:187], v[120:123]
	v_mfma_f32_16x16x32_bf16 v[108:111], v[144:147], v[192:195], v[108:111]
	v_mfma_f32_16x16x32_bf16 v[104:107], v[160:163], v[192:195], v[104:107]
	v_mfma_f32_16x16x32_bf16 v[92:95], v[144:147], v[200:203], v[92:95]
	v_mfma_f32_16x16x32_bf16 v[88:91], v[160:163], v[200:203], v[88:91]
	v_mfma_f32_16x16x32_bf16 v[76:79], v[144:147], v[208:211], v[76:79]
	v_mfma_f32_16x16x32_bf16 v[72:75], v[160:163], v[208:211], v[72:75]
	v_mfma_f32_16x16x32_bf16 v[124:127], v[156:159], v[188:191], v[124:127]
	v_mfma_f32_16x16x32_bf16 v[120:123], v[164:167], v[188:191], v[120:123]
	v_mfma_f32_16x16x32_bf16 v[108:111], v[156:159], v[196:199], v[108:111]
	v_mfma_f32_16x16x32_bf16 v[104:107], v[164:167], v[196:199], v[104:107]
	v_mfma_f32_16x16x32_bf16 v[92:95], v[156:159], v[204:207], v[92:95]
	v_mfma_f32_16x16x32_bf16 v[88:91], v[164:167], v[204:207], v[88:91]
	v_mfma_f32_16x16x32_bf16 v[76:79], v[156:159], v[212:215], v[76:79]
	v_mfma_f32_16x16x32_bf16 v[72:75], v[164:167], v[212:215], v[72:75]
	s_setprio 0
	s_setprio 1
	v_mfma_f32_16x16x32_bf16 v[116:119], v[168:171], v[184:187], v[116:119]
	v_mfma_f32_16x16x32_bf16 v[112:115], v[176:179], v[184:187], v[112:115]
	v_mfma_f32_16x16x32_bf16 v[100:103], v[168:171], v[192:195], v[100:103]
	v_mfma_f32_16x16x32_bf16 v[96:99], v[176:179], v[192:195], v[96:99]
	v_mfma_f32_16x16x32_bf16 v[84:87], v[168:171], v[200:203], v[84:87]
	v_mfma_f32_16x16x32_bf16 v[80:83], v[176:179], v[200:203], v[80:83]
	v_mfma_f32_16x16x32_bf16 v[68:71], v[168:171], v[208:211], v[68:71]
	v_mfma_f32_16x16x32_bf16 v[64:67], v[176:179], v[208:211], v[64:67]
	v_mfma_f32_16x16x32_bf16 v[116:119], v[172:175], v[188:191], v[116:119]
	v_mfma_f32_16x16x32_bf16 v[112:115], v[180:183], v[188:191], v[112:115]
	v_mfma_f32_16x16x32_bf16 v[100:103], v[172:175], v[196:199], v[100:103]
	v_mfma_f32_16x16x32_bf16 v[96:99], v[180:183], v[196:199], v[96:99]
	v_mfma_f32_16x16x32_bf16 v[84:87], v[172:175], v[204:207], v[84:87]
	v_mfma_f32_16x16x32_bf16 v[80:83], v[180:183], v[204:207], v[80:83]
	v_mfma_f32_16x16x32_bf16 v[68:71], v[172:175], v[212:215], v[68:71]
	v_mfma_f32_16x16x32_bf16 v[64:67], v[180:183], v[212:215], v[64:67]
	s_setprio 0
	s_waitcnt vmcnt(8)
	s_barrier
	s_add_i32 s30, s55, s36
	v_lshl_add_u64 v[148:149], v[148:149], 0, s[6:7]
	s_mov_b32 m0, s30
	ds_read_b128 v[184:187], v155 offset:49152
	ds_read_b128 v[188:191], v155 offset:50176
	ds_read_b128 v[192:195], v155 offset:51200
	ds_read_b128 v[196:199], v155 offset:52224
	ds_read_b128 v[200:203], v155 offset:53248
	ds_read_b128 v[204:207], v155 offset:54272
	ds_read_b128 v[208:211], v155 offset:55296
	ds_read_b128 v[212:215], v155 offset:56320
	global_load_lds_dwordx4 v[148:149], off
	s_add_i32 m0, s30, 0x2000
	s_add_u32 s28, s28, 0x100080
	v_lshl_add_u64 v[148:149], v[216:217], 0, s[6:7]
	s_addc_u32 s29, s29, 0
	s_add_i32 s30, s56, s36
	global_load_lds_dwordx4 v[148:149], off
	v_lshl_add_u64 v[148:149], s[28:29], 0, v[130:131]
	s_mov_b32 m0, s30
	s_nop 0
	global_load_lds_dwordx4 v[148:149], off
	v_lshl_add_u64 v[148:149], s[28:29], 0, v[134:135]
	s_add_i32 m0, s30, 0x2000
	s_nop 0
	global_load_lds_dwordx4 v[148:149], off
	v_lshl_add_u64 v[148:149], v[218:219], 0, s[6:7]
	s_mov_b32 m0, s42
	s_nop 0
	global_load_lds_dwordx4 v[148:149], off
	v_lshl_add_u64 v[148:149], v[220:221], 0, s[6:7]
	s_mov_b32 m0, s44
	s_nop 0
	global_load_lds_dwordx4 v[148:149], off
	s_cmp_lg_u64 s[8:9], 0
	s_cbranch_scc1 .Llw_4
	s_waitcnt vmcnt(8)
.Llw_4:
	s_waitcnt lgkmcnt(0)
	s_barrier
	s_setprio 1
	s_waitcnt lgkmcnt(0)
	v_mfma_f32_16x16x32_bf16 v[60:63], v[144:147], v[184:187], v[60:63]
	v_mfma_f32_16x16x32_bf16 v[56:59], v[160:163], v[184:187], v[56:59]
	v_mfma_f32_16x16x32_bf16 v[44:47], v[144:147], v[192:195], v[44:47]
	v_mfma_f32_16x16x32_bf16 v[40:43], v[160:163], v[192:195], v[40:43]
	v_mfma_f32_16x16x32_bf16 v[28:31], v[144:147], v[200:203], v[28:31]
	v_mfma_f32_16x16x32_bf16 v[24:27], v[160:163], v[200:203], v[24:27]
	v_mfma_f32_16x16x32_bf16 v[12:15], v[144:147], v[208:211], v[12:15]
	v_mfma_f32_16x16x32_bf16 v[8:11], v[160:163], v[208:211], v[8:11]
	v_mfma_f32_16x16x32_bf16 v[60:63], v[156:159], v[188:191], v[60:63]
	v_mfma_f32_16x16x32_bf16 v[56:59], v[164:167], v[188:191], v[56:59]
	v_mfma_f32_16x16x32_bf16 v[44:47], v[156:159], v[196:199], v[44:47]
	v_mfma_f32_16x16x32_bf16 v[40:43], v[164:167], v[196:199], v[40:43]
	v_mfma_f32_16x16x32_bf16 v[28:31], v[156:159], v[204:207], v[28:31]
	v_mfma_f32_16x16x32_bf16 v[24:27], v[164:167], v[204:207], v[24:27]
	v_mfma_f32_16x16x32_bf16 v[12:15], v[156:159], v[212:215], v[12:15]
	v_mfma_f32_16x16x32_bf16 v[8:11], v[164:167], v[212:215], v[8:11]
	s_setprio 0
	s_setprio 1
	v_mfma_f32_16x16x32_bf16 v[52:55], v[168:171], v[184:187], v[52:55]
	v_mfma_f32_16x16x32_bf16 v[48:51], v[176:179], v[184:187], v[48:51]
	v_mfma_f32_16x16x32_bf16 v[36:39], v[168:171], v[192:195], v[36:39]
	v_mfma_f32_16x16x32_bf16 v[32:35], v[176:179], v[192:195], v[32:35]
	v_mfma_f32_16x16x32_bf16 v[20:23], v[168:171], v[200:203], v[20:23]
	v_mfma_f32_16x16x32_bf16 v[16:19], v[176:179], v[200:203], v[16:19]
	v_mfma_f32_16x16x32_bf16 v[4:7], v[168:171], v[208:211], v[4:7]
	v_mfma_f32_16x16x32_bf16 v[0:3], v[176:179], v[208:211], v[0:3]
	v_mfma_f32_16x16x32_bf16 v[52:55], v[172:175], v[188:191], v[52:55]
	v_mfma_f32_16x16x32_bf16 v[48:51], v[180:183], v[188:191], v[48:51]
	v_mfma_f32_16x16x32_bf16 v[36:39], v[172:175], v[196:199], v[36:39]
	v_mfma_f32_16x16x32_bf16 v[32:35], v[180:183], v[196:199], v[32:35]
	v_mfma_f32_16x16x32_bf16 v[20:23], v[172:175], v[204:207], v[20:23]
	v_mfma_f32_16x16x32_bf16 v[16:19], v[180:183], v[204:207], v[16:19]
	v_mfma_f32_16x16x32_bf16 v[4:7], v[172:175], v[212:215], v[4:7]
	v_mfma_f32_16x16x32_bf16 v[0:3], v[180:183], v[212:215], v[0:3]
	s_setprio 0
	s_waitcnt vmcnt(8)
	s_barrier
	s_add_i32 s54, s54, 2
	s_add_u32 s26, s26, 0x100
	s_addc_u32 s27, s27, 0
	s_add_u32 s25, s25, 0x100
	s_addc_u32 s53, s53, 0
	s_cmp_gt_u32 s54, 61
	s_cbranch_scc0 .LBB0_1369
	s_and_b64 vcc, exec, s[8:9]
	s_cbranch_vccz .LBB0_1372
	s_barrier

; #define PG8_STAGE(bufoff, gbase, voff) do { _Pragma("unroll") for (int _i = 0; _i < 2; ++_i) \
;         __builtin_amdgcn_global_load_lds((const unsigned*)((const char*)(gbase) + (voff)[_i]), (PG8_LAS unsigned*)(lds + (bufoff) + ldsw + _i * 8192), 16, 0, 0); } while (0)
; #define PG8_LDA(dst, b, h) do { _Pragma("unroll") for (int m = 0; m < 4; ++m) _Pragma("unroll") for (int k = 0; k < 2; ++k) dst[m][k] = *(const PG8_LAS bf16x8*)(lds + PG8_SA(b, h) + aoff + m * 2048 + k * 1024); } while (0)
; #define PG8_LDB(dst, b, h) do { _Pragma("unroll") for (int n = 0; n < 2; ++n) _Pragma("unroll") for (int k = 0; k < 2; ++k) dst[n][k] = *(const PG8_LAS bf16x8*)(lds + PG8_SB(b, h) + boff + n * 2048 + k * 1024); } while (0)
; #define PG8_MMA(ai, bj, At, Bt) do { __builtin_amdgcn_s_setprio(1); _Pragma("unroll") for (int m = 0; m < 4; ++m) _Pragma("unroll") for (int n = 0; n < 2; ++n) _Pragma("unroll") for (int k = 0; k < 2; ++k) \
;         acc[ai][bj][m][n] = __builtin_amdgcn_mfma_f32_16x16x32_bf16(Bt[n][k], At[m][k], acc[ai][bj][m][n], 0, 0, 0); __builtin_amdgcn_s_setprio(0); } while (0)
; #define PG8_WAIT_V(n) asm volatile("s_waitcnt vmcnt(" #n ")" ::: "memory")
; #define PG8_WAIT_L(n) asm volatile("s_waitcnt lgkmcnt(" #n ")" ::: "memory")
; #define PG8_BAR __builtin_amdgcn_s_barrier()
; #define PG8_SCHED __builtin_amdgcn_sched_barrier(0)
; template <class Epi, class Sched, bool ALIGN_EPI = false, bool SP2 = false>
; __device__ __forceinline__ void gemm_phase(PG8_LAS unsigned char* lds, const Gemm g, const Sched& S, const Epi& E, int tid_in) {
;     ...
;             PG8_LDB(B0, 0, 0); PG8_LDB(B1, 0, 1); PG8_SCHED; PG8_LDA(At, 0, 0); PG8_STAGE(PG8_SA(1, 1), a1 + hstep, voffA);
;             PG8_WAIT_V(8); PG8_WAIT_L(0); PG8_BAR; PG8_MMA(0, 0, At, B0); PG8_MMA(0, 1, At, B1); PG8_BAR; PG8_SCHED;
;             PG8_LDA(At, 0, 1); PG8_STAGE(PG8_SB(0, 0), b2, voffB); PG8_STAGE(PG8_SB(0, 1), b2 + hstep, voffB); PG8_STAGE(PG8_SA(0, 0), a2, voffA);
;             PG8_WAIT_V(8); PG8_WAIT_L(0); PG8_BAR; PG8_MMA(1, 0, At, B0); PG8_MMA(1, 1, At, B1); PG8_BAR; PG8_SCHED;
.LBB0_1551:
	ds_read_b128 v[150:153], v147
	ds_read_b128 v[154:157], v147 offset:1024
	ds_read_b128 v[158:161], v147 offset:2048
	ds_read_b128 v[162:165], v147 offset:3072
	ds_read_b128 v[166:169], v148
	ds_read_b128 v[170:173], v148 offset:1024
	ds_read_b128 v[174:177], v148 offset:2048
	ds_read_b128 v[178:181], v148 offset:3072
	s_add_u32 s34, s30, 0xfff00080
	s_addc_u32 s35, s31, -1
	s_cmp_eq_u32 s60, 60
	s_cselect_b32 s37, s21, s35
	s_cselect_b32 s36, s56, s34
	s_cselect_b32 s35, s19, s59
	s_cselect_b32 s34, s57, s58
	v_lshl_add_u64 v[142:143], s[30:31], 0, v[136:137]
	s_add_i32 m0, s29, 0xc000
	ds_read_b128 v[182:185], v149
	ds_read_b128 v[186:189], v149 offset:1024
	ds_read_b128 v[190:193], v149 offset:2048
	ds_read_b128 v[194:197], v149 offset:3072
	ds_read_b128 v[198:201], v149 offset:4096
	ds_read_b128 v[202:205], v149 offset:5120
	ds_read_b128 v[206:209], v149 offset:6144
	ds_read_b128 v[210:213], v149 offset:7168
	global_load_lds_dwordx4 v[142:143], off
	v_lshl_add_u64 v[142:143], s[30:31], 0, v[138:139]
	s_add_i32 m0, s29, 0xe000
	s_nop 0
	global_load_lds_dwordx4 v[142:143], off
	s_cmp_lg_u64 s[8:9], 0
	s_cbranch_scc1 .Llw_11
	s_waitcnt vmcnt(8)
.Llw_11:
	s_waitcnt lgkmcnt(0)
	s_barrier
	s_setprio 1
	s_waitcnt lgkmcnt(0)
	v_mfma_f32_16x16x32_bf16 v[124:127], v[150:153], v[182:185], v[124:127]
	v_mfma_f32_16x16x32_bf16 v[120:123], v[158:161], v[182:185], v[120:123]
	v_mfma_f32_16x16x32_bf16 v[112:115], v[150:153], v[190:193], v[112:115]
	v_mfma_f32_16x16x32_bf16 v[104:107], v[158:161], v[190:193], v[104:107]
	v_mfma_f32_16x16x32_bf16 v[96:99], v[150:153], v[198:201], v[96:99]
	v_mfma_f32_16x16x32_bf16 v[88:91], v[158:161], v[198:201], v[88:91]
	v_mfma_f32_16x16x32_bf16 v[80:83], v[150:153], v[206:209], v[80:83]
	v_mfma_f32_16x16x32_bf16 v[72:75], v[158:161], v[206:209], v[72:75]
	v_mfma_f32_16x16x32_bf16 v[124:127], v[154:157], v[186:189], v[124:127]
	v_mfma_f32_16x16x32_bf16 v[120:123], v[162:165], v[186:189], v[120:123]
	v_mfma_f32_16x16x32_bf16 v[112:115], v[154:157], v[194:197], v[112:115]
	v_mfma_f32_16x16x32_bf16 v[104:107], v[162:165], v[194:197], v[104:107]
	v_mfma_f32_16x16x32_bf16 v[96:99], v[154:157], v[202:205], v[96:99]
	v_mfma_f32_16x16x32_bf16 v[88:91], v[162:165], v[202:205], v[88:91]
	v_mfma_f32_16x16x32_bf16 v[80:83], v[154:157], v[210:213], v[80:83]
	v_mfma_f32_16x16x32_bf16 v[72:75], v[162:165], v[210:213], v[72:75]
	s_setprio 0
	s_setprio 1
	v_mfma_f32_16x16x32_bf16 v[116:119], v[166:169], v[182:185], v[116:119]
	v_mfma_f32_16x16x32_bf16 v[108:111], v[174:177], v[182:185], v[108:111]
	v_mfma_f32_16x16x32_bf16 v[100:103], v[166:169], v[190:193], v[100:103]
	v_mfma_f32_16x16x32_bf16 v[92:95], v[174:177], v[190:193], v[92:95]
	v_mfma_f32_16x16x32_bf16 v[84:87], v[166:169], v[198:201], v[84:87]
	v_mfma_f32_16x16x32_bf16 v[76:79], v[174:177], v[198:201], v[76:79]
	v_mfma_f32_16x16x32_bf16 v[68:71], v[166:169], v[206:209], v[68:71]
	v_mfma_f32_16x16x32_bf16 v[64:67], v[174:177], v[206:209], v[64:67]
	v_mfma_f32_16x16x32_bf16 v[116:119], v[170:173], v[186:189], v[116:119]
	v_mfma_f32_16x16x32_bf16 v[108:111], v[178:181], v[186:189], v[108:111]
	v_mfma_f32_16x16x32_bf16 v[100:103], v[170:173], v[194:197], v[100:103]
	v_mfma_f32_16x16x32_bf16 v[92:95], v[178:181], v[194:197], v[92:95]
	v_mfma_f32_16x16x32_bf16 v[84:87], v[170:173], v[202:205], v[84:87]
	v_mfma_f32_16x16x32_bf16 v[76:79], v[178:181], v[202:205], v[76:79]
	v_mfma_f32_16x16x32_bf16 v[68:71], v[170:173], v[210:213], v[68:71]
	v_mfma_f32_16x16x32_bf16 v[64:67], v[178:181], v[210:213], v[64:67]
	s_setprio 0
	s_waitcnt vmcnt(8)
	s_barrier
	s_add_i32 s61, s49, s40
	v_lshl_add_u64 v[142:143], s[34:35], 0, v[132:133]
	s_mov_b32 m0, s61
	ds_read_b128 v[182:185], v149 offset:16384
	ds_read_b128 v[186:189], v149 offset:17408
	ds_read_b128 v[190:193], v149 offset:18432
	ds_read_b128 v[194:197], v149 offset:19456
	ds_read_b128 v[198:201], v149 offset:20480
	ds_read_b128 v[202:205], v149 offset:21504
	ds_read_b128 v[206:209], v149 offset:22528
	ds_read_b128 v[210:213], v149 offset:23552
	global_load_lds_dwordx4 v[142:143], off
	s_add_i32 m0, s61, 0x2000
	s_add_u32 s62, s34, 0x100000
	v_lshl_add_u64 v[214:215], s[34:35], 0, v[128:129]
	s_addc_u32 s63, s35, 0
	s_add_i32 s61, s50, s40
	global_load_lds_dwordx4 v[214:215], off
	v_lshl_add_u64 v[216:217], s[62:63], 0, v[132:133]
	s_mov_b32 m0, s61
	v_lshl_add_u64 v[218:219], s[36:37], 0, v[130:131]
	global_load_lds_dwordx4 v[216:217], off
	v_lshl_add_u64 v[216:217], s[62:63], 0, v[128:129]
	s_add_i32 m0, s61, 0x2000
	s_nop 0
	global_load_lds_dwordx4 v[216:217], off
	v_lshl_add_u64 v[216:217], s[36:37], 0, v[134:135]
	s_mov_b32 m0, s29
	s_nop 0
	global_load_lds_dwordx4 v[216:217], off
	s_mov_b32 m0, s43
	s_nop 0
	global_load_lds_dwordx4 v[218:219], off
	s_cmp_lg_u64 s[8:9], 0
	s_cbranch_scc1 .Llw_10
	s_waitcnt vmcnt(8)
; #define PG8_STAGE(bufoff, gbase, voff) do { _Pragma("unroll") for (int _i = 0; _i < 2; ++_i) \
;         __builtin_amdgcn_global_load_lds((const unsigned*)((const char*)(gbase) + (voff)[_i]), (PG8_LAS unsigned*)(lds + (bufoff) + ldsw + _i * 8192), 16, 0, 0); } while (0)
; #define PG8_LDA(dst, b, h) do { _Pragma("unroll") for (int m = 0; m < 4; ++m) _Pragma("unroll") for (int k = 0; k < 2; ++k) dst[m][k] = *(const PG8_LAS bf16x8*)(lds + PG8_SA(b, h) + aoff + m * 2048 + k * 1024); } while (0)
; #define PG8_LDB(dst, b, h) do { _Pragma("unroll") for (int n = 0; n < 2; ++n) _Pragma("unroll") for (int k = 0; k < 2; ++k) dst[n][k] = *(const PG8_LAS bf16x8*)(lds + PG8_SB(b, h) + boff + n * 2048 + k * 1024); } while (0)
; #define PG8_MMA(ai, bj, At, Bt) do { __builtin_amdgcn_s_setprio(1); _Pragma("unroll") for (int m = 0; m < 4; ++m) _Pragma("unroll") for (int n = 0; n < 2; ++n) _Pragma("unroll") for (int k = 0; k < 2; ++k) \
;         acc[ai][bj][m][n] = __builtin_amdgcn_mfma_f32_16x16x32_bf16(Bt[n][k], At[m][k], acc[ai][bj][m][n], 0, 0, 0); __builtin_amdgcn_s_setprio(0); } while (0)
; #define PG8_WAIT_V(n) asm volatile("s_waitcnt vmcnt(" #n ")" ::: "memory")
; #define PG8_WAIT_L(n) asm volatile("s_waitcnt lgkmcnt(" #n ")" ::: "memory")
; #define PG8_BAR __builtin_amdgcn_s_barrier()
; #define PG8_SCHED __builtin_amdgcn_sched_barrier(0)
; template <class Epi, class Sched, bool ALIGN_EPI = false, bool SP2 = false>
; __device__ __forceinline__ void gemm_phase(PG8_LAS unsigned char* lds, const Gemm g, const Sched& S, const Epi& E, int tid_in) {
;     ...
;             PG8_WAIT_V(8); PG8_WAIT_L(0); PG8_BAR; PG8_MMA(1, 0, At, B0); PG8_MMA(1, 1, At, B1); PG8_BAR; PG8_SCHED;
;             PG8_LDB(B0, 1, 0); PG8_LDB(B1, 1, 1); PG8_SCHED; PG8_LDA(At, 1, 0); PG8_STAGE(PG8_SA(0, 1), a2 + hstep, voffA);
;             PG8_WAIT_V(8); PG8_WAIT_L(0); PG8_BAR; PG8_MMA(0, 0, At, B0); PG8_MMA(0, 1, At, B1); PG8_BAR; PG8_SCHED;
.Llw_10:
	s_waitcnt lgkmcnt(0)
	s_barrier
	s_setprio 1
	s_waitcnt lgkmcnt(0)
	v_mfma_f32_16x16x32_bf16 v[60:63], v[150:153], v[182:185], v[60:63]
	v_mfma_f32_16x16x32_bf16 v[56:59], v[158:161], v[182:185], v[56:59]
	v_mfma_f32_16x16x32_bf16 v[48:51], v[150:153], v[190:193], v[48:51]
	v_mfma_f32_16x16x32_bf16 v[40:43], v[158:161], v[190:193], v[40:43]
	v_mfma_f32_16x16x32_bf16 v[32:35], v[150:153], v[198:201], v[32:35]
	v_mfma_f32_16x16x32_bf16 v[24:27], v[158:161], v[198:201], v[24:27]
	v_mfma_f32_16x16x32_bf16 v[16:19], v[150:153], v[206:209], v[16:19]
	v_mfma_f32_16x16x32_bf16 v[8:11], v[158:161], v[206:209], v[8:11]
	v_mfma_f32_16x16x32_bf16 v[60:63], v[154:157], v[186:189], v[60:63]
	v_mfma_f32_16x16x32_bf16 v[56:59], v[162:165], v[186:189], v[56:59]
	v_mfma_f32_16x16x32_bf16 v[48:51], v[154:157], v[194:197], v[48:51]
	v_mfma_f32_16x16x32_bf16 v[40:43], v[162:165], v[194:197], v[40:43]
	v_mfma_f32_16x16x32_bf16 v[32:35], v[154:157], v[202:205], v[32:35]
	v_mfma_f32_16x16x32_bf16 v[24:27], v[162:165], v[202:205], v[24:27]
	v_mfma_f32_16x16x32_bf16 v[16:19], v[154:157], v[210:213], v[16:19]
	v_mfma_f32_16x16x32_bf16 v[8:11], v[162:165], v[210:213], v[8:11]
	s_setprio 0
	s_setprio 1
	v_mfma_f32_16x16x32_bf16 v[52:55], v[166:169], v[182:185], v[52:55]
	v_mfma_f32_16x16x32_bf16 v[44:47], v[174:177], v[182:185], v[44:47]
	v_mfma_f32_16x16x32_bf16 v[36:39], v[166:169], v[190:193], v[36:39]
	v_mfma_f32_16x16x32_bf16 v[28:31], v[174:177], v[190:193], v[28:31]
	v_mfma_f32_16x16x32_bf16 v[20:23], v[166:169], v[198:201], v[20:23]
	v_mfma_f32_16x16x32_bf16 v[12:15], v[174:177], v[198:201], v[12:15]
	v_mfma_f32_16x16x32_bf16 v[4:7], v[166:169], v[206:209], v[4:7]
	v_mfma_f32_16x16x32_bf16 v[0:3], v[174:177], v[206:209], v[0:3]
	v_mfma_f32_16x16x32_bf16 v[52:55], v[170:173], v[186:189], v[52:55]
	v_mfma_f32_16x16x32_bf16 v[44:47], v[178:181], v[186:189], v[44:47]
	v_mfma_f32_16x16x32_bf16 v[36:39], v[170:173], v[194:197], v[36:39]
	v_mfma_f32_16x16x32_bf16 v[28:31], v[178:181], v[194:197], v[28:31]
	v_mfma_f32_16x16x32_bf16 v[20:23], v[170:173], v[202:205], v[20:23]
	v_mfma_f32_16x16x32_bf16 v[12:15], v[178:181], v[202:205], v[12:15]
	v_mfma_f32_16x16x32_bf16 v[4:7], v[170:173], v[210:213], v[4:7]
	v_mfma_f32_16x16x32_bf16 v[0:3], v[178:181], v[210:213], v[0:3]
	s_setprio 0
	s_waitcnt vmcnt(8)
	s_barrier
	s_add_i32 s61, 0, 0x18000
	s_add_i32 s62, 0, 0x1c000
	v_add_u32_e32 v162, s61, v145
	v_add_u32_e32 v178, s62, v145
	ds_read_b128 v[150:153], v162
	ds_read_b128 v[154:157], v162 offset:1024
	ds_read_b128 v[158:161], v162 offset:2048
	ds_read_b128 v[162:165], v162 offset:3072
	ds_read_b128 v[166:169], v178
	ds_read_b128 v[170:173], v178 offset:1024
	ds_read_b128 v[174:177], v178 offset:2048
	ds_read_b128 v[178:181], v178 offset:3072
	s_add_u32 s36, s36, 0x100000
	s_addc_u32 s37, s37, 0
	s_mov_b32 m0, s44
	v_lshl_add_u64 v[220:221], s[36:37], 0, v[134:135]
	ds_read_b128 v[182:185], v149 offset:32768
	ds_read_b128 v[186:189], v149 offset:33792
	ds_read_b128 v[190:193], v149 offset:34816
	ds_read_b128 v[194:197], v149 offset:35840
	ds_read_b128 v[198:201], v149 offset:36864
	ds_read_b128 v[202:205], v149 offset:37888
	ds_read_b128 v[206:209], v149 offset:38912
	ds_read_b128 v[210:213], v149 offset:39936
	global_load_lds_dwordx4 v[220:221], off
	v_lshl_add_u64 v[220:221], s[36:37], 0, v[130:131]
	s_mov_b32 m0, s45
	s_nop 0
	global_load_lds_dwordx4 v[220:221], off
	s_cmp_lg_u64 s[8:9], 0
	s_cbranch_scc1 .Llw_9
	s_waitcnt vmcnt(8)
; #define PG8_STAGE(bufoff, gbase, voff) do { _Pragma("unroll") for (int _i = 0; _i < 2; ++_i) \
;         __builtin_amdgcn_global_load_lds((const unsigned*)((const char*)(gbase) + (voff)[_i]), (PG8_LAS unsigned*)(lds + (bufoff) + ldsw + _i * 8192), 16, 0, 0); } while (0)
; #define PG8_LDA(dst, b, h) do { _Pragma("unroll") for (int m = 0; m < 4; ++m) _Pragma("unroll") for (int k = 0; k < 2; ++k) dst[m][k] = *(const PG8_LAS bf16x8*)(lds + PG8_SA(b, h) + aoff + m * 2048 + k * 1024); } while (0)
; #define PG8_MMA(ai, bj, At, Bt) do { __builtin_amdgcn_s_setprio(1); _Pragma("unroll") for (int m = 0; m < 4; ++m) _Pragma("unroll") for (int n = 0; n < 2; ++n) _Pragma("unroll") for (int k = 0; k < 2; ++k) \
;         acc[ai][bj][m][n] = __builtin_amdgcn_mfma_f32_16x16x32_bf16(Bt[n][k], At[m][k], acc[ai][bj][m][n], 0, 0, 0); __builtin_amdgcn_s_setprio(0); } while (0)
; #define PG8_WAIT_V(n) asm volatile("s_waitcnt vmcnt(" #n ")" ::: "memory")
; #define PG8_WAIT_L(n) asm volatile("s_waitcnt lgkmcnt(" #n ")" ::: "memory")
; #define PG8_BAR __builtin_amdgcn_s_barrier()
; #define PG8_SCHED __builtin_amdgcn_sched_barrier(0)
; template <class Epi, class Sched, bool ALIGN_EPI = false, bool SP2 = false>
; __device__ __forceinline__ void gemm_phase(PG8_LAS unsigned char* lds, const Gemm g, const Sched& S, const Epi& E, int tid_in) {
;     ...
;             PG8_WAIT_V(8); PG8_WAIT_L(0); PG8_BAR; PG8_MMA(0, 0, At, B0); PG8_MMA(0, 1, At, B1); PG8_BAR; PG8_SCHED;
;             PG8_LDA(At, 1, 1); PG8_STAGE(PG8_SB(1, 0), b3, voffB); PG8_STAGE(PG8_SB(1, 1), b3 + hstep, voffB); PG8_STAGE(PG8_SA(1, 0), a3, voffA);
;             PG8_WAIT_V(8); PG8_WAIT_L(0); PG8_BAR; PG8_MMA(1, 0, At, B0); PG8_MMA(1, 1, At, B1); PG8_BAR; PG8_SCHED;
.Llw_9:
	s_waitcnt lgkmcnt(0)
	s_barrier
	s_setprio 1
	s_waitcnt lgkmcnt(0)
	v_mfma_f32_16x16x32_bf16 v[124:127], v[150:153], v[182:185], v[124:127]
	v_mfma_f32_16x16x32_bf16 v[120:123], v[158:161], v[182:185], v[120:123]
	v_mfma_f32_16x16x32_bf16 v[112:115], v[150:153], v[190:193], v[112:115]
	v_mfma_f32_16x16x32_bf16 v[104:107], v[158:161], v[190:193], v[104:107]
	v_mfma_f32_16x16x32_bf16 v[96:99], v[150:153], v[198:201], v[96:99]
	v_mfma_f32_16x16x32_bf16 v[88:91], v[158:161], v[198:201], v[88:91]
	v_mfma_f32_16x16x32_bf16 v[80:83], v[150:153], v[206:209], v[80:83]
	v_mfma_f32_16x16x32_bf16 v[72:75], v[158:161], v[206:209], v[72:75]
	v_mfma_f32_16x16x32_bf16 v[124:127], v[154:157], v[186:189], v[124:127]
	v_mfma_f32_16x16x32_bf16 v[120:123], v[162:165], v[186:189], v[120:123]
	v_mfma_f32_16x16x32_bf16 v[112:115], v[154:157], v[194:197], v[112:115]
	v_mfma_f32_16x16x32_bf16 v[104:107], v[162:165], v[194:197], v[104:107]
	v_mfma_f32_16x16x32_bf16 v[96:99], v[154:157], v[202:205], v[96:99]
	v_mfma_f32_16x16x32_bf16 v[88:91], v[162:165], v[202:205], v[88:91]
	v_mfma_f32_16x16x32_bf16 v[80:83], v[154:157], v[210:213], v[80:83]
	v_mfma_f32_16x16x32_bf16 v[72:75], v[162:165], v[210:213], v[72:75]
	s_setprio 0
	s_setprio 1
	v_mfma_f32_16x16x32_bf16 v[116:119], v[166:169], v[182:185], v[116:119]
	v_mfma_f32_16x16x32_bf16 v[108:111], v[174:177], v[182:185], v[108:111]
	v_mfma_f32_16x16x32_bf16 v[100:103], v[166:169], v[190:193], v[100:103]
	v_mfma_f32_16x16x32_bf16 v[92:95], v[174:177], v[190:193], v[92:95]
	v_mfma_f32_16x16x32_bf16 v[84:87], v[166:169], v[198:201], v[84:87]
	v_mfma_f32_16x16x32_bf16 v[76:79], v[174:177], v[198:201], v[76:79]
	v_mfma_f32_16x16x32_bf16 v[68:71], v[166:169], v[206:209], v[68:71]
	v_mfma_f32_16x16x32_bf16 v[64:67], v[174:177], v[206:209], v[64:67]
	v_mfma_f32_16x16x32_bf16 v[116:119], v[170:173], v[186:189], v[116:119]
	v_mfma_f32_16x16x32_bf16 v[108:111], v[178:181], v[186:189], v[108:111]
	v_mfma_f32_16x16x32_bf16 v[100:103], v[170:173], v[194:197], v[100:103]
	v_mfma_f32_16x16x32_bf16 v[92:95], v[178:181], v[194:197], v[92:95]
	v_mfma_f32_16x16x32_bf16 v[84:87], v[170:173], v[202:205], v[84:87]
	v_mfma_f32_16x16x32_bf16 v[76:79], v[178:181], v[202:205], v[76:79]
	v_mfma_f32_16x16x32_bf16 v[68:71], v[170:173], v[210:213], v[68:71]
	v_mfma_f32_16x16x32_bf16 v[64:67], v[178:181], v[210:213], v[64:67]
	s_setprio 0
	s_waitcnt vmcnt(8)
	s_barrier
	s_add_i32 s36, s61, s40
	v_lshl_add_u64 v[142:143], v[142:143], 0, s[6:7]
	s_mov_b32 m0, s36
	ds_read_b128 v[182:185], v149 offset:49152
	ds_read_b128 v[186:189], v149 offset:50176
	ds_read_b128 v[190:193], v149 offset:51200
	ds_read_b128 v[194:197], v149 offset:52224
	ds_read_b128 v[198:201], v149 offset:53248
	ds_read_b128 v[202:205], v149 offset:54272
	ds_read_b128 v[206:209], v149 offset:55296
	ds_read_b128 v[210:213], v149 offset:56320
	global_load_lds_dwordx4 v[142:143], off
	s_add_i32 m0, s36, 0x2000
	s_add_u32 s34, s34, 0x100080
	v_lshl_add_u64 v[142:143], v[214:215], 0, s[6:7]
	s_addc_u32 s35, s35, 0
	s_add_i32 s36, s62, s40
	global_load_lds_dwordx4 v[142:143], off
	v_lshl_add_u64 v[142:143], s[34:35], 0, v[132:133]
	s_mov_b32 m0, s36
	s_nop 0
	global_load_lds_dwordx4 v[142:143], off
	v_lshl_add_u64 v[142:143], s[34:35], 0, v[128:129]
	s_add_i32 m0, s36, 0x2000
	s_nop 0
	global_load_lds_dwordx4 v[142:143], off
	v_lshl_add_u64 v[142:143], v[216:217], 0, s[6:7]
	s_mov_b32 m0, s47
	s_nop 0
	global_load_lds_dwordx4 v[142:143], off
	v_lshl_add_u64 v[142:143], v[218:219], 0, s[6:7]
	s_mov_b32 m0, s48
	s_nop 0
	global_load_lds_dwordx4 v[142:143], off
	s_cmp_lg_u64 s[8:9], 0
	s_cbranch_scc1 .Llw_8
	s_waitcnt vmcnt(8)
.Llw_8:
	s_waitcnt lgkmcnt(0)
	s_barrier
	s_setprio 1
	s_waitcnt lgkmcnt(0)
	v_mfma_f32_16x16x32_bf16 v[60:63], v[150:153], v[182:185], v[60:63]
	v_mfma_f32_16x16x32_bf16 v[56:59], v[158:161], v[182:185], v[56:59]
	v_mfma_f32_16x16x32_bf16 v[48:51], v[150:153], v[190:193], v[48:51]
	v_mfma_f32_16x16x32_bf16 v[40:43], v[158:161], v[190:193], v[40:43]
	v_mfma_f32_16x16x32_bf16 v[32:35], v[150:153], v[198:201], v[32:35]
	v_mfma_f32_16x16x32_bf16 v[24:27], v[158:161], v[198:201], v[24:27]
	v_mfma_f32_16x16x32_bf16 v[16:19], v[150:153], v[206:209], v[16:19]
	v_mfma_f32_16x16x32_bf16 v[8:11], v[158:161], v[206:209], v[8:11]
	v_mfma_f32_16x16x32_bf16 v[60:63], v[154:157], v[186:189], v[60:63]
	v_mfma_f32_16x16x32_bf16 v[56:59], v[162:165], v[186:189], v[56:59]
	v_mfma_f32_16x16x32_bf16 v[48:51], v[154:157], v[194:197], v[48:51]
	v_mfma_f32_16x16x32_bf16 v[40:43], v[162:165], v[194:197], v[40:43]
	v_mfma_f32_16x16x32_bf16 v[32:35], v[154:157], v[202:205], v[32:35]
	v_mfma_f32_16x16x32_bf16 v[24:27], v[162:165], v[202:205], v[24:27]
	v_mfma_f32_16x16x32_bf16 v[16:19], v[154:157], v[210:213], v[16:19]
	v_mfma_f32_16x16x32_bf16 v[8:11], v[162:165], v[210:213], v[8:11]
	s_setprio 0
	s_setprio 1
	v_mfma_f32_16x16x32_bf16 v[52:55], v[166:169], v[182:185], v[52:55]
	v_mfma_f32_16x16x32_bf16 v[44:47], v[174:177], v[182:185], v[44:47]
	v_mfma_f32_16x16x32_bf16 v[36:39], v[166:169], v[190:193], v[36:39]
	v_mfma_f32_16x16x32_bf16 v[28:31], v[174:177], v[190:193], v[28:31]
	v_mfma_f32_16x16x32_bf16 v[20:23], v[166:169], v[198:201], v[20:23]
	v_mfma_f32_16x16x32_bf16 v[12:15], v[174:177], v[198:201], v[12:15]
	v_mfma_f32_16x16x32_bf16 v[4:7], v[166:169], v[206:209], v[4:7]
	v_mfma_f32_16x16x32_bf16 v[0:3], v[174:177], v[206:209], v[0:3]
	v_mfma_f32_16x16x32_bf16 v[52:55], v[170:173], v[186:189], v[52:55]
	v_mfma_f32_16x16x32_bf16 v[44:47], v[178:181], v[186:189], v[44:47]
	v_mfma_f32_16x16x32_bf16 v[36:39], v[170:173], v[194:197], v[36:39]
	v_mfma_f32_16x16x32_bf16 v[28:31], v[178:181], v[194:197], v[28:31]
	v_mfma_f32_16x16x32_bf16 v[20:23], v[170:173], v[202:205], v[20:23]
	v_mfma_f32_16x16x32_bf16 v[12:15], v[178:181], v[202:205], v[12:15]
	v_mfma_f32_16x16x32_bf16 v[4:7], v[170:173], v[210:213], v[4:7]
	v_mfma_f32_16x16x32_bf16 v[0:3], v[178:181], v[210:213], v[0:3]
	s_setprio 0
	s_waitcnt vmcnt(8)
	s_barrier
	s_add_i32 s60, s60, 2
	s_add_u32 s30, s30, 0x100
	s_addc_u32 s31, s31, 0
	s_add_u32 s58, s58, 0x100
	s_addc_u32 s59, s59, 0
	s_cmp_gt_u32 s60, 61
	s_cbranch_scc0 .LBB0_1551
	s_and_b64 vcc, exec, s[8:9]
	s_cbranch_vccz .LBB0_1554
	s_barrier
